# HGRN pass-1 item: first barrier removed plus dead scalar address arithmetic of the current item deleted
# baseline (speedup 1.0000x reference)
; DEV float bf2f(u16 h) { return __uint_as_float(((unsigned)h) << 16); }
; DEV float flog(float x) { return __builtin_amdgcn_logf(x) * 0.6931471805599453f; }
; DEV void hg_load_k(const u16* __restrict__ zb, int tid, u16 (&kr)[16]) {
;   const int wid = tid >> 6, lane = tid & 63, dir = wid >> 2, qu = wid & 3;
;   const u16* kp = zb + (long)(qu * 16) * NINP + C_HF + dir * 512 + lane;
; #pragma unroll
;   for (int i = 0; i < 16; ++i) kr[i] = kp[(long)i * NINP];
; }
; DEV void hg_load_v(const u16* __restrict__ zb, int wid, int lane, u16 (&vr)[8]) {
;   const u16* vp = zb + (long)(wid * 8) * NINP + C_HI + lane;
; #pragma unroll
;   for (int i = 0; i < 8; ++i) vr[i] = vp[(long)i * NINP];
; }
; DEV void hg_prep(int dir, int qu, int lane, char* smem, const u16 (&kr)[16], float (&g)[16], float (&kk)[16]) {
; #pragma unroll
;   for (int i = 0; i < 16; ++i) {
;     kk[i] = bf2f(kr[i]);
;     g[i] = fmaxf(flog(1.f - kk[i]), -20.f);
;   }
;   float total;
;   if (dir == 0) {
; #pragma unroll
;     for (int i = 1; i < 16; ++i) g[i] += g[i - 1];
;     total = g[15];
;   } else {
; #pragma unroll
;     for (int i = 14; i >= 0; --i) g[i] += g[i + 1];
.LBB0_734:
	v_readlane_b32 s6, v253, 2
	s_mov_b32 s11, s10
	s_add_i32 s10, s10, s6
	v_readlane_b32 s7, v253, 3
	s_cmpk_gt_i32 s10, 0x8ff
	s_cselect_b64 s[6:7], -1, 0
	s_cmpk_lt_i32 s10, 0x900
	s_cselect_b32 s8, s10, s11
	s_mov_b32 s50, s8
	s_ashr_i32 s9, s11, 3
	s_and_b32 s8, s11, 7
	s_mul_hi_i32 s11, s9, 0x38e38e39
	s_lshr_b32 s12, s11, 31
	s_ashr_i32 s11, s11, 3
	s_add_i32 s11, s11, s12
	s_lshl_b32 s12, s11, 3
	s_or_b32 s8, s12, s8
	s_mul_i32 s11, s11, 36
	s_mul_i32 s8, s8, 36
	s_sub_i32 s9, s9, s11
	s_add_i32 s8, s8, s9
	s_mul_hi_i32 s9, s8, 0x38e38e39
	s_lshr_b32 s11, s9, 31
	s_ashr_i32 s9, s9, 3
	s_add_i32 s11, s9, s11
	s_mul_i32 s9, s11, 36
	s_sub_i32 s12, s8, s9
	v_lshlrev_b32_e32 v56, 16, v7
	v_and_b32_e32 v57, 0xffff0000, v7
	v_sub_f32_e32 v7, 1.0, v56
	v_log_f32_e32 v7, v7
	v_lshlrev_b32_e32 v46, 16, v6
	v_and_b32_e32 v47, 0xffff0000, v6
	s_mov_b32 s8, s50
	s_and_b32 s9, s8, 7
	s_ashr_i32 s8, s8, 3
	s_mul_hi_i32 s51, s8, 0x38e38e39
	s_lshr_b32 s13, s51, 31
	s_ashr_i32 s51, s51, 3
	s_add_i32 s51, s51, s13
	s_lshl_b32 s13, s51, 3
	s_or_b32 s9, s13, s9
	s_mul_i32 s51, s51, 36
	s_mul_i32 s9, s9, 36
	s_sub_i32 s8, s8, s51
	s_add_i32 s9, s9, s8
	s_mul_hi_i32 s8, s9, 0x38e38e39
	s_lshr_b32 s51, s8, 31
	s_ashr_i32 s8, s8, 3
	s_add_i32 s8, s8, s51
	s_mul_i32 s51, s8, 36
	s_sub_i32 s9, s9, s51
	s_ashr_i32 s51, s8, 3
	s_lshl_b32 s9, s9, 6
	s_mul_hi_i32 s13, s51, 0x900
	s_mulk_i32 s51, 0x900
	s_ashr_i32 s15, s9, 31
	s_add_u32 s9, s51, s9
	s_addc_u32 s51, s13, s15
	s_mulk_i32 s51, 0x4400
	s_mul_hi_u32 s13, s9, 0x4400
	s_add_i32 s13, s13, s51
	s_mulk_i32 s9, 0x4400
	s_add_u32 s9, s88, s9
	s_addc_u32 s51, s89, s13
	s_lshl_b32 s8, s8, 7
	s_and_b32 s8, s8, 0x380
	s_add_u32 s8, s9, s8
	s_addc_u32 s9, s51, 0
	global_load_ushort v41, v112, s[8:9] offset:2880
	global_load_ushort v81, v113, s[8:9] offset:3904
	global_load_ushort v82, v114, s[8:9] offset:832
	global_load_ushort v83, v115, s[8:9] offset:1856
	global_load_ushort v84, v116, s[8:9] offset:2880
	global_load_ushort v85, v117, s[8:9] offset:3904
	global_load_ushort v86, v118, s[8:9] offset:832
	global_load_ushort v87, v119, s[8:9] offset:1856
	v_lshl_add_u64 v[8:9], s[8:9], 0, v[156:157]
	v_lshl_add_u64 v[8:9], v[32:33], 1, v[8:9]
	v_mov_b32_e32 v190, v40
	v_mov_b32_e32 v191, v157
	v_lshl_add_u64 v[8:9], v[8:9], 0, v[190:191]
	s_movk_i32 s8, 0x5000
	v_add_co_u32_e32 v10, vcc, s8, v8
	s_mov_b32 s19, 0x9000
	s_nop 0
	v_addc_co_u32_e32 v11, vcc, 0, v9, vcc
	v_add_co_u32_e32 v12, vcc, s19, v8
	s_mov_b32 s18, 0xd000
	s_nop 0
	v_addc_co_u32_e32 v13, vcc, 0, v9, vcc
	v_add_co_u32_e32 v14, vcc, s18, v8
	s_mov_b32 s17, 0x11000
	s_nop 0
	v_addc_co_u32_e32 v15, vcc, 0, v9, vcc
	v_add_co_u32_e32 v16, vcc, s17, v8
	s_mov_b32 s16, 0x1e000
	s_nop 0
	v_addc_co_u32_e32 v17, vcc, 0, v9, vcc
	v_add_co_u32_e32 v18, vcc, s68, v8
	s_mov_b32 s8, 0x22000
	s_nop 0
	v_addc_co_u32_e32 v19, vcc, 0, v9, vcc
	v_add_co_u32_e32 v20, vcc, s73, v8
	s_nop 0
	v_addc_co_u32_e32 v21, vcc, 0, v9, vcc
	v_add_co_u32_e32 v22, vcc, s16, v8
	v_and_b32_e32 v49, 0xffff0000, v0
	s_nop 0
	v_addc_co_u32_e32 v23, vcc, 0, v9, vcc
	global_load_ushort v65, v[8:9], off offset:3904
	global_load_ushort v66, v[10:11], off offset:832
	global_load_ushort v67, v[12:13], off offset:1856
	global_load_ushort v68, v[14:15], off offset:2880
	global_load_ushort v69, v[16:17], off offset:3904
	global_load_ushort v70, v[18:19], off offset:832
	global_load_ushort v71, v[20:21], off offset:1856
	global_load_ushort v72, v[22:23], off offset:2880
	v_add_co_u32_e32 v10, vcc, s8, v8
	s_mov_b32 s8, 0x27000
	s_nop 0
	v_addc_co_u32_e32 v11, vcc, 0, v9, vcc
	v_add_co_u32_e32 v12, vcc, s8, v8
	s_mov_b32 s8, 0x2b000
	s_nop 0
	v_addc_co_u32_e32 v13, vcc, 0, v9, vcc
	v_add_co_u32_e32 v14, vcc, s8, v8
	s_mov_b32 s8, 0x2f000
	s_nop 0
	v_addc_co_u32_e32 v15, vcc, 0, v9, vcc
	v_add_co_u32_e32 v16, vcc, s8, v8
	s_mov_b32 s8, 0x33000
	s_nop 0
	v_addc_co_u32_e32 v17, vcc, 0, v9, vcc
	v_add_co_u32_e32 v18, vcc, s8, v8
	s_mov_b32 s8, 0x38000
	s_nop 0
	v_addc_co_u32_e32 v19, vcc, 0, v9, vcc
	v_add_co_u32_e32 v20, vcc, s8, v8
	s_mov_b32 s8, 0x3c000
	s_nop 0
	v_addc_co_u32_e32 v21, vcc, 0, v9, vcc
	v_add_co_u32_e32 v22, vcc, s8, v8
	s_mov_b32 s8, 0x40000
	s_nop 0
	v_addc_co_u32_e32 v23, vcc, 0, v9, vcc
	v_add_co_u32_e32 v8, vcc, s8, v8
	v_addc_co_u32_e32 v9, vcc, 0, v9, vcc
	global_load_ushort v73, v[10:11], off offset:3904
	global_load_ushort v74, v[12:13], off offset:832
	global_load_ushort v75, v[14:15], off offset:1856
	global_load_ushort v76, v[16:17], off offset:2880
	global_load_ushort v77, v[18:19], off offset:3904
	global_load_ushort v78, v[20:21], off offset:832
	global_load_ushort v79, v[22:23], off offset:1856
	global_load_ushort v80, v[8:9], off offset:2880
	v_sub_f32_e32 v8, 1.0, v49
	v_log_f32_e32 v8, v8
	v_sub_f32_e32 v9, 1.0, v57
	v_log_f32_e32 v9, v9
	v_sub_f32_e32 v6, 1.0, v46
	v_mul_f32_e32 v8, 0x3f317218, v8
	v_max_f32_e32 v88, 0xc1a00000, v8
	v_log_f32_e32 v6, v6
	v_sub_f32_e32 v8, 1.0, v47
	v_log_f32_e32 v8, v8
	v_mul_f32_e32 v7, 0x3f317218, v7
	v_lshlrev_b32_e32 v54, 16, v5
	v_max_f32_e32 v89, 0xc1a00000, v7
	v_mul_f32_e32 v7, 0x3f317218, v9
	v_and_b32_e32 v55, 0xffff0000, v5
	v_sub_f32_e32 v5, 1.0, v54
	v_max_f32_e32 v90, 0xc1a00000, v7
	v_mul_f32_e32 v6, 0x3f317218, v6
	v_log_f32_e32 v7, v5
	v_sub_f32_e32 v5, 1.0, v55
	v_max_f32_e32 v91, 0xc1a00000, v6
	v_mul_f32_e32 v6, 0x3f317218, v8
	v_log_f32_e32 v8, v5
	v_lshlrev_b32_e32 v44, 16, v4
	v_and_b32_e32 v45, 0xffff0000, v4
	v_sub_f32_e32 v4, 1.0, v44
	v_max_f32_e32 v5, 0xc1a00000, v6
	v_mul_f32_e32 v6, 0x3f317218, v7
	v_mul_f32_e32 v7, 0x3f317218, v8
	v_log_f32_e32 v4, v4
	v_sub_f32_e32 v8, 1.0, v45
	v_log_f32_e32 v9, v8
	v_lshlrev_b32_e32 v52, 16, v3
	v_mul_f32_e32 v4, 0x3f317218, v4
	v_and_b32_e32 v53, 0xffff0000, v3
	v_sub_f32_e32 v3, 1.0, v52
	v_max_f32_e32 v8, 0xc1a00000, v4
	v_mul_f32_e32 v4, 0x3f317218, v9
	v_log_f32_e32 v3, v3
	v_sub_f32_e32 v9, 1.0, v53
	v_log_f32_e32 v11, v9
	v_lshlrev_b32_e32 v42, 16, v2
	v_mul_f32_e32 v3, 0x3f317218, v3
	v_lshlrev_b32_e32 v50, 16, v1
	v_lshlrev_b32_e32 v48, 16, v0
	v_max_f32_e32 v10, 0xc1a00000, v3
	v_mul_f32_e32 v3, 0x3f317218, v11
	v_and_b32_e32 v43, 0xffff0000, v2
	v_sub_f32_e32 v2, 1.0, v42
	v_and_b32_e32 v51, 0xffff0000, v1
	v_sub_f32_e32 v1, 1.0, v50
	v_sub_f32_e32 v0, 1.0, v48
	v_max_f32_e32 v9, 0xc1a00000, v4
	v_log_f32_e32 v2, v2
	v_sub_f32_e32 v4, 1.0, v43
	v_max_f32_e32 v11, 0xc1a00000, v3
	v_log_f32_e32 v1, v1
	v_sub_f32_e32 v3, 1.0, v51
	v_log_f32_e32 v0, v0
	v_log_f32_e32 v4, v4
	v_log_f32_e32 v3, v3
	v_mul_f32_e32 v2, 0x3f317218, v2
	v_mul_f32_e32 v1, 0x3f317218, v1
	v_mul_f32_e32 v0, 0x3f317218, v0
	v_max_f32_e32 v12, 0xc1a00000, v2
	v_mul_f32_e32 v2, 0x3f317218, v4
	v_max_f32_e32 v14, 0xc1a00000, v1
	v_mul_f32_e32 v1, 0x3f317218, v3
	v_max_f32_e32 v0, 0xc1a00000, v0
	v_max_f32_e32 v6, 0xc1a00000, v6
	v_max_f32_e32 v7, 0xc1a00000, v7
	v_max_f32_e32 v13, 0xc1a00000, v2
	v_max_f32_e32 v15, 0xc1a00000, v1
	s_and_saveexec_b64 s[8:9], s[40:41]
	s_xor_b64 s[8:9], exec, s[8:9]
	s_cbranch_execz .LBB0_736
; DEV void hg_prep(int dir, int qu, int lane, char* smem, const u16 (&kr)[16], float (&g)[16], float (&kk)[16]) {
;     ...
;   } else {
; #pragma unroll
;     for (int i = 14; i >= 0; --i) g[i] += g[i + 1];
;     total = g[0];
	v_add_f32_e32 v14, v14, v15
	v_add_f32_e32 v13, v13, v14
	v_add_f32_e32 v12, v12, v13
	v_add_f32_e32 v11, v11, v12
	v_add_f32_e32 v10, v10, v11
	v_add_f32_e32 v9, v9, v10
	v_add_f32_e32 v8, v8, v9
	v_add_f32_e32 v7, v7, v8
	v_add_f32_e32 v6, v6, v7
	v_add_f32_e32 v5, v5, v6
	v_add_f32_e32 v4, v91, v5
	v_add_f32_e32 v3, v90, v4
	v_add_f32_e32 v2, v89, v3
	v_add_f32_e32 v1, v88, v2
	v_add_f32_e32 v0, v0, v1
	v_mov_b64_e32 v[30:31], v[14:15]
	v_mov_b64_e32 v[28:29], v[12:13]
	v_mov_b64_e32 v[26:27], v[10:11]
	v_mov_b64_e32 v[24:25], v[8:9]
	v_mov_b64_e32 v[22:23], v[6:7]
	v_mov_b64_e32 v[20:21], v[4:5]
	v_mov_b64_e32 v[18:19], v[2:3]
	v_mov_b64_e32 v[16:17], v[0:1]
